# opt11 + attention softmax: NaN-canonicalising v_max x,x triples folded, sum seeds 0+e0 folded, lrun copy folded into v_fma (bit-identical for non-NaN)
# speedup vs baseline: 1.0202x; 1.0060x over previous
; __device__ __forceinline__ float xhalf_max(float m) { auto rr = __builtin_amdgcn_permlane32_swap(__float_as_uint(m), __float_as_uint(m), false, false); return fmaxf(__uint_as_float(rr[0]), __uint_as_float(rr[1])); }
.LBB0_862:
	v_max_f32_e32 v34, v16, v17
	v_max_f32_e32 v37, v0, v1
	v_max3_f32 v34, v34, v18, v19
	v_max3_f32 v37, v37, v2, v3
	v_max3_f32 v34, v34, v20, v21
	v_max3_f32 v37, v37, v4, v5
	v_max3_f32 v34, v34, v22, v23
	v_max3_f32 v37, v37, v6, v7
	v_max3_f32 v34, v34, v24, v25
	v_max3_f32 v37, v37, v8, v9
	v_max3_f32 v34, v34, v26, v27
	v_max3_f32 v37, v37, v10, v11
	v_max3_f32 v34, v34, v28, v29
	v_max3_f32 v37, v37, v12, v13
	v_max3_f32 v34, v34, v30, v31
	v_max3_f32 v37, v37, v14, v15
	v_add_f32_e32 v34, v35, v34
	v_add_f32_e32 v37, v36, v37
	v_max_f32_e32 v34, v34, v37
	v_mov_b32_e32 v37, v34
	s_nop 1
	v_permlane32_swap_b32_e32 v34, v37
	v_max_f32_e32 v34, v34, v37
	v_add_f32_e32 v37, 0x7f800000, v34
	v_cmp_gt_f32_e32 vcc, s18, v37
	s_cmp_lg_u64 vcc, exec
	s_cselect_b64 s[82:83], -1, 0
	s_cmp_eq_u64 vcc, exec
	s_cbranch_scc1 .LBB0_864
	v_max_f32_e32 v34, v34, v34
	v_max_f32_e32 v112, 0xff800000, v34
	v_sub_f32_e32 v51, v112, v35
	v_sub_f32_e32 v52, v112, v36
	v_sub_f32_e32 v16, v16, v51
	v_sub_f32_e32 v0, v0, v52
	v_exp_f32_e32 v34, v16
	v_exp_f32_e32 v35, v0
	v_sub_f32_e32 v0, v17, v51
	v_sub_f32_e32 v1, v1, v52
	v_exp_f32_e32 v0, v0
	v_exp_f32_e32 v1, v1
	v_sub_f32_e32 v16, v18, v51
	v_sub_f32_e32 v2, v2, v52
	v_exp_f32_e32 v36, v16
	v_exp_f32_e32 v37, v2
	v_sub_f32_e32 v2, v19, v51
	v_sub_f32_e32 v3, v3, v52
	v_exp_f32_e32 v2, v2
	v_exp_f32_e32 v3, v3
	v_sub_f32_e32 v18, v20, v51
	v_sub_f32_e32 v4, v4, v52
	v_pk_add_f32 v[16:17], v[34:35], 0 op_sel_hi:[1,0]
	v_exp_f32_e32 v38, v18
	v_exp_f32_e32 v39, v4
	v_sub_f32_e32 v4, v21, v51
	v_sub_f32_e32 v5, v5, v52
	v_pk_add_f32 v[16:17], v[0:1], v[16:17]
	v_exp_f32_e32 v4, v4
	v_exp_f32_e32 v5, v5
	v_sub_f32_e32 v18, v22, v51
	v_sub_f32_e32 v6, v6, v52
	v_pk_add_f32 v[16:17], v[36:37], v[16:17]
	v_exp_f32_e32 v40, v18
	v_exp_f32_e32 v41, v6
	v_sub_f32_e32 v6, v23, v51
	v_sub_f32_e32 v7, v7, v52
	v_pk_add_f32 v[16:17], v[2:3], v[16:17]
	v_exp_f32_e32 v6, v6
	v_exp_f32_e32 v7, v7
	v_sub_f32_e32 v18, v24, v51
	v_sub_f32_e32 v8, v8, v52
	v_exp_f32_e32 v42, v18
	v_exp_f32_e32 v43, v8
	v_sub_f32_e32 v8, v25, v51
	v_sub_f32_e32 v9, v9, v52
	v_pk_add_f32 v[16:17], v[38:39], v[16:17]
	v_exp_f32_e32 v8, v8
	v_exp_f32_e32 v9, v9
	v_sub_f32_e32 v18, v26, v51
	v_sub_f32_e32 v10, v10, v52
	v_pk_add_f32 v[16:17], v[4:5], v[16:17]
	v_exp_f32_e32 v44, v18
	v_exp_f32_e32 v45, v10
	v_sub_f32_e32 v10, v27, v51
	v_sub_f32_e32 v11, v11, v52
	v_pk_add_f32 v[16:17], v[40:41], v[16:17]
	v_exp_f32_e32 v10, v10
	v_exp_f32_e32 v11, v11
	v_sub_f32_e32 v18, v28, v51
	v_sub_f32_e32 v12, v12, v52
	v_pk_add_f32 v[16:17], v[6:7], v[16:17]
	v_sub_f32_e32 v50, 0xff800000, v112
	v_exp_f32_e32 v46, v18
	v_exp_f32_e32 v47, v12
	v_sub_f32_e32 v12, v29, v51
	v_sub_f32_e32 v13, v13, v52
	v_sub_f32_e32 v18, v30, v51
	v_pk_add_f32 v[16:17], v[42:43], v[16:17]
	v_exp_f32_e32 v12, v12
	v_exp_f32_e32 v13, v13
	v_exp_f32_e32 v48, v18
	v_sub_f32_e32 v14, v14, v52
	v_pk_add_f32 v[16:17], v[8:9], v[16:17]
	v_exp_f32_e32 v18, v50
	v_exp_f32_e32 v49, v14
	v_sub_f32_e32 v14, v31, v51
	v_sub_f32_e32 v15, v15, v52
	v_pk_add_f32 v[16:17], v[44:45], v[16:17]
	v_exp_f32_e32 v14, v14
	v_exp_f32_e32 v15, v15
	v_pk_add_f32 v[16:17], v[10:11], v[16:17]
	v_cmp_neq_f32_e32 vcc, 1.0, v18
	v_pk_add_f32 v[16:17], v[46:47], v[16:17]
	s_cmp_lg_u64 vcc, 0
	v_pk_add_f32 v[16:17], v[12:13], v[16:17]
	v_mul_f32_e32 v19, 0, v18
	v_pk_add_f32 v[16:17], v[48:49], v[16:17]
	s_cselect_b64 vcc, -1, 0
	v_pk_add_f32 v[16:17], v[14:15], v[16:17]
	v_cvt_pk_bf16_f32 v144, v34, v0
	v_add_f32_e32 v193, v16, v17
	v_cndmask_b32_e32 v16, 0, v19, vcc
	v_fmac_f32_e32 v193, 0, v18
	v_mov_b32_e32 v17, v16
	v_mov_b32_e32 v18, v16
	v_mov_b32_e32 v19, v16
	v_mov_b32_e32 v20, v16
	v_mov_b32_e32 v21, v16
	v_mov_b32_e32 v22, v16
	v_mov_b32_e32 v23, v16
	v_mov_b32_e32 v24, v16
	v_mov_b32_e32 v25, v16
	v_mov_b32_e32 v26, v16
	v_mov_b32_e32 v27, v16
	v_mov_b32_e32 v28, v16
	v_mov_b32_e32 v29, v16
	v_mov_b32_e32 v30, v16
	v_mov_b32_e32 v31, v16
	v_cvt_pk_bf16_f32 v145, v36, v2
	v_cvt_pk_bf16_f32 v146, v38, v4
	v_cvt_pk_bf16_f32 v147, v40, v6
	v_cvt_pk_bf16_f32 v148, v42, v8
	v_cvt_pk_bf16_f32 v149, v44, v10
	v_cvt_pk_bf16_f32 v150, v46, v12
	v_cvt_pk_bf16_f32 v151, v48, v14
	v_cvt_pk_bf16_f32 v152, v35, v1
	v_cvt_pk_bf16_f32 v153, v37, v3
	v_cvt_pk_bf16_f32 v154, v39, v5
	v_cvt_pk_bf16_f32 v155, v41, v7
	v_cvt_pk_bf16_f32 v156, v43, v9
	v_cvt_pk_bf16_f32 v157, v45, v11
	v_cvt_pk_bf16_f32 v158, v47, v13
	v_cvt_pk_bf16_f32 v159, v49, v15
	s_branch .LBB0_865

.LBB0_876:
	v_max_f32_e32 v96, v80, v81
	v_max_f32_e32 v99, v64, v65
	v_max3_f32 v96, v96, v82, v83
	v_max3_f32 v99, v99, v66, v67
	v_max3_f32 v96, v96, v84, v85
	v_max3_f32 v99, v99, v68, v69
	v_max3_f32 v96, v96, v86, v87
	v_max3_f32 v99, v99, v70, v71
	v_max3_f32 v96, v96, v88, v89
	v_max3_f32 v99, v99, v72, v73
	v_max3_f32 v96, v96, v90, v91
	v_max3_f32 v99, v99, v74, v75
	v_max3_f32 v96, v96, v92, v93
	v_max3_f32 v99, v99, v76, v77
	v_max3_f32 v96, v96, v94, v95
	v_max3_f32 v99, v99, v78, v79
	v_add_f32_e32 v96, v97, v96
	v_add_f32_e32 v99, v98, v99
	v_max_f32_e32 v96, v96, v99
	v_mov_b32_e32 v99, v96
	s_nop 1
	v_permlane32_swap_b32_e32 v96, v99
	v_max_f32_e32 v96, v96, v99
	v_sub_f32_e32 v99, v96, v112
	v_cmp_gt_f32_e32 vcc, s18, v99
	s_cmp_lg_u64 vcc, exec
	s_cselect_b64 s[78:79], -1, 0
	s_cmp_eq_u64 vcc, exec
	s_cbranch_scc1 .LBB0_880
	v_max_f32_e32 v203, v112, v96
	v_sub_f32_e32 v96, v112, v203
	v_exp_f32_e32 v96, v96
	s_nop 0
	v_cmp_neq_f32_e32 vcc, 1.0, v96
	s_cbranch_vccz .LBB0_879
	v_mul_f32_e32 v30, v96, v30
	v_mul_f32_e32 v31, v96, v31
	v_mul_f32_e32 v28, v96, v28
	v_mul_f32_e32 v29, v96, v29
	v_mul_f32_e32 v26, v96, v26
	v_mul_f32_e32 v27, v96, v27
	v_mul_f32_e32 v24, v96, v24
	v_mul_f32_e32 v25, v96, v25
	v_mul_f32_e32 v22, v96, v22
	v_mul_f32_e32 v23, v96, v23
	v_mul_f32_e32 v20, v96, v20
	v_mul_f32_e32 v21, v96, v21
	v_mul_f32_e32 v18, v96, v18
	v_mul_f32_e32 v19, v96, v19
	v_mul_f32_e32 v16, v96, v16
	v_mul_f32_e32 v17, v96, v17
	v_mul_f32_e32 v62, v96, v62
	v_mul_f32_e32 v63, v96, v63
	v_mul_f32_e32 v60, v96, v60
	v_mul_f32_e32 v61, v96, v61
	v_mul_f32_e32 v58, v96, v58
	v_mul_f32_e32 v59, v96, v59
	v_mul_f32_e32 v56, v96, v56
	v_mul_f32_e32 v57, v96, v57
	v_mul_f32_e32 v54, v96, v54
	v_mul_f32_e32 v55, v96, v55
	v_mul_f32_e32 v52, v96, v52
	v_mul_f32_e32 v53, v96, v53
	v_mul_f32_e32 v50, v96, v50
	v_mul_f32_e32 v51, v96, v51
	v_mul_f32_e32 v48, v96, v48
	v_mul_f32_e32 v49, v96, v49
	v_mul_f32_e32 v46, v96, v46
	v_mul_f32_e32 v47, v96, v47
	v_mul_f32_e32 v44, v96, v44
	v_mul_f32_e32 v45, v96, v45
	v_mul_f32_e32 v42, v96, v42
	v_mul_f32_e32 v43, v96, v43
	v_mul_f32_e32 v40, v96, v40
	v_mul_f32_e32 v41, v96, v41
	v_mul_f32_e32 v38, v96, v38
	v_mul_f32_e32 v39, v96, v39
	v_mul_f32_e32 v36, v96, v36
	v_mul_f32_e32 v37, v96, v37
	v_mul_f32_e32 v34, v96, v34
	v_mul_f32_e32 v35, v96, v35
	v_mul_f32_e32 v32, v96, v32
	v_mul_f32_e32 v33, v96, v33
	v_mul_f32_e32 v14, v96, v14
	v_mul_f32_e32 v15, v96, v15
	v_mul_f32_e32 v12, v96, v12
	v_mul_f32_e32 v13, v96, v13
	v_mul_f32_e32 v10, v96, v10
	v_mul_f32_e32 v11, v96, v11
	v_mul_f32_e32 v8, v96, v8
	v_mul_f32_e32 v9, v96, v9
	v_mul_f32_e32 v6, v96, v6
	v_mul_f32_e32 v7, v96, v7
	v_mul_f32_e32 v4, v96, v4
	v_mul_f32_e32 v5, v96, v5
	v_mul_f32_e32 v2, v96, v2
	v_mul_f32_e32 v3, v96, v3
	v_mul_f32_e32 v0, v96, v0
	v_mul_f32_e32 v1, v96, v1
.LBB0_879:
	v_sub_f32_e32 v97, v203, v97
	v_sub_f32_e32 v98, v203, v98
	v_sub_f32_e32 v80, v80, v97
	v_sub_f32_e32 v64, v64, v98
	v_exp_f32_e32 v80, v80
	v_exp_f32_e32 v64, v64
	v_sub_f32_e32 v81, v81, v97
	v_sub_f32_e32 v65, v65, v98
	v_exp_f32_e32 v81, v81
	v_exp_f32_e32 v65, v65
	v_sub_f32_e32 v82, v82, v97
	v_sub_f32_e32 v66, v66, v98
	v_exp_f32_e32 v82, v82
	v_exp_f32_e32 v66, v66
	v_sub_f32_e32 v83, v83, v97
	v_sub_f32_e32 v67, v67, v98
	v_exp_f32_e32 v83, v83
	v_exp_f32_e32 v67, v67
	v_sub_f32_e32 v84, v84, v97
	v_sub_f32_e32 v68, v68, v98
	v_exp_f32_e32 v84, v84
	v_exp_f32_e32 v68, v68
	v_sub_f32_e32 v85, v85, v97
	v_sub_f32_e32 v69, v69, v98
	v_add_f32_e32 v99, v81, v80
	v_add_f32_e32 v100, v65, v64
	v_exp_f32_e32 v85, v85
	v_exp_f32_e32 v69, v69
	v_sub_f32_e32 v86, v86, v97
	v_sub_f32_e32 v70, v70, v98
	v_add_f32_e32 v99, v82, v99
	v_add_f32_e32 v100, v66, v100
	v_exp_f32_e32 v86, v86
	v_exp_f32_e32 v70, v70
	v_sub_f32_e32 v87, v87, v97
	v_sub_f32_e32 v71, v71, v98
	v_add_f32_e32 v99, v83, v99
	v_add_f32_e32 v100, v67, v100
	v_exp_f32_e32 v87, v87
	v_exp_f32_e32 v71, v71
	v_sub_f32_e32 v88, v88, v97
	v_sub_f32_e32 v72, v72, v98
	v_add_f32_e32 v99, v84, v99
	v_add_f32_e32 v100, v68, v100
	v_exp_f32_e32 v88, v88
	v_exp_f32_e32 v72, v72
	v_sub_f32_e32 v89, v89, v97
	v_sub_f32_e32 v73, v73, v98
	v_add_f32_e32 v99, v85, v99
	v_add_f32_e32 v100, v69, v100
	v_exp_f32_e32 v89, v89
	v_exp_f32_e32 v73, v73
	v_sub_f32_e32 v90, v90, v97
	v_sub_f32_e32 v74, v74, v98
	v_add_f32_e32 v99, v86, v99
	v_add_f32_e32 v100, v70, v100
	v_exp_f32_e32 v90, v90
	v_exp_f32_e32 v74, v74
	v_sub_f32_e32 v91, v91, v97
	v_sub_f32_e32 v75, v75, v98
	v_add_f32_e32 v99, v87, v99
	v_add_f32_e32 v100, v71, v100
	v_exp_f32_e32 v91, v91
	v_exp_f32_e32 v75, v75
	v_sub_f32_e32 v92, v92, v97
	v_sub_f32_e32 v76, v76, v98
	v_add_f32_e32 v99, v88, v99
	v_add_f32_e32 v100, v72, v100
	v_exp_f32_e32 v92, v92
	v_exp_f32_e32 v76, v76
	v_sub_f32_e32 v93, v93, v97
	v_sub_f32_e32 v77, v77, v98
	v_add_f32_e32 v99, v89, v99
	v_add_f32_e32 v100, v73, v100
	v_exp_f32_e32 v93, v93
	v_exp_f32_e32 v77, v77
	v_sub_f32_e32 v94, v94, v97
	v_sub_f32_e32 v78, v78, v98
	v_add_f32_e32 v99, v90, v99
	v_add_f32_e32 v100, v74, v100
	v_exp_f32_e32 v94, v94
	v_exp_f32_e32 v78, v78
	v_sub_f32_e32 v95, v95, v97
	v_sub_f32_e32 v79, v79, v98
	v_add_f32_e32 v99, v91, v99
	v_add_f32_e32 v100, v75, v100
	v_exp_f32_e32 v95, v95
	v_exp_f32_e32 v79, v79
	v_add_f32_e32 v99, v92, v99
	v_add_f32_e32 v100, v76, v100
	v_add_f32_e32 v99, v93, v99
	v_add_f32_e32 v100, v77, v100
	v_add_f32_e32 v97, v94, v99
	v_add_f32_e32 v98, v78, v100
	v_add_f32_e32 v97, v95, v97
	v_add_f32_e32 v98, v79, v98
	v_add_f32_e32 v97, v97, v98
	v_fma_f32 v193, v193, v96, v97
	v_cvt_pk_bf16_f32 v144, v80, v81
	v_cvt_pk_bf16_f32 v145, v82, v83
	v_cvt_pk_bf16_f32 v146, v84, v85
	v_cvt_pk_bf16_f32 v147, v86, v87
	v_cvt_pk_bf16_f32 v148, v88, v89
	v_cvt_pk_bf16_f32 v149, v90, v91
	v_cvt_pk_bf16_f32 v150, v92, v93
	v_cvt_pk_bf16_f32 v151, v94, v95
	v_cvt_pk_bf16_f32 v152, v64, v65
	v_cvt_pk_bf16_f32 v153, v66, v67
	v_cvt_pk_bf16_f32 v154, v68, v69
	v_cvt_pk_bf16_f32 v155, v70, v71
	v_cvt_pk_bf16_f32 v156, v72, v73
	v_cvt_pk_bf16_f32 v157, v74, v75
	v_cvt_pk_bf16_f32 v158, v76, v77
	v_cvt_pk_bf16_f32 v159, v78, v79
	s_andn2_b64 vcc, exec, s[78:79]
	s_cbranch_vccz .LBB0_881
	s_branch .LBB0_882

.LBB0_897:
	v_max_f32_e32 v174, v112, v113
	v_max_f32_e32 v179, v96, v97
	v_max3_f32 v174, v174, v114, v115
	v_max3_f32 v179, v179, v98, v99
	v_max3_f32 v174, v174, v116, v117
	v_max3_f32 v179, v179, v100, v101
	v_max3_f32 v174, v174, v118, v119
	v_max3_f32 v179, v179, v102, v103
	v_max3_f32 v174, v174, v120, v121
	v_max3_f32 v179, v179, v104, v105
	v_max3_f32 v174, v174, v122, v123
	v_max3_f32 v179, v179, v106, v107
	v_max3_f32 v174, v174, v124, v125
	v_max3_f32 v179, v179, v108, v109
	v_max3_f32 v174, v174, v126, v127
	v_max3_f32 v179, v179, v110, v111
	v_add_f32_e32 v174, v204, v174
	v_add_f32_e32 v179, v205, v179
	v_max_f32_e32 v174, v174, v179
	v_mov_b32_e32 v179, v174
	s_nop 1
	v_permlane32_swap_b32_e32 v174, v179
	v_max_f32_e32 v174, v174, v179
	v_sub_f32_e32 v179, v174, v203
	v_cmp_gt_f32_e32 vcc, s18, v179
	s_cmp_lg_u64 vcc, exec
	s_cselect_b64 s[82:83], -1, 0
	s_cmp_eq_u64 vcc, exec
	s_cbranch_scc1 .LBB0_901
	v_max_f32_e32 v144, v174, v174
	v_max_f32_e32 v145, v203, v203
	v_max_f32_e32 v174, v145, v144
	v_sub_f32_e32 v144, v203, v174
	v_exp_f32_e32 v144, v144
	s_nop 0
	v_cmp_neq_f32_e32 vcc, 1.0, v144
	s_cbranch_vccz .LBB0_900
	v_mul_f32_e32 v30, v144, v30
	v_mul_f32_e32 v31, v144, v31
	v_mul_f32_e32 v28, v144, v28
	v_mul_f32_e32 v29, v144, v29
	v_mul_f32_e32 v26, v144, v26
	v_mul_f32_e32 v27, v144, v27
	v_mul_f32_e32 v24, v144, v24
	v_mul_f32_e32 v25, v144, v25
	v_mul_f32_e32 v22, v144, v22
	v_mul_f32_e32 v23, v144, v23
	v_mul_f32_e32 v20, v144, v20
	v_mul_f32_e32 v21, v144, v21
	v_mul_f32_e32 v18, v144, v18
	v_mul_f32_e32 v19, v144, v19
	v_mul_f32_e32 v16, v144, v16
	v_mul_f32_e32 v17, v144, v17
	v_mul_f32_e32 v62, v144, v62
	v_mul_f32_e32 v63, v144, v63
	v_mul_f32_e32 v60, v144, v60
	v_mul_f32_e32 v61, v144, v61
	v_mul_f32_e32 v58, v144, v58
	v_mul_f32_e32 v59, v144, v59
	v_mul_f32_e32 v56, v144, v56
	v_mul_f32_e32 v57, v144, v57
	v_mul_f32_e32 v54, v144, v54
	v_mul_f32_e32 v55, v144, v55
	v_mul_f32_e32 v52, v144, v52
	v_mul_f32_e32 v53, v144, v53
	v_mul_f32_e32 v50, v144, v50
	v_mul_f32_e32 v51, v144, v51
	v_mul_f32_e32 v48, v144, v48
	v_mul_f32_e32 v49, v144, v49
	v_mul_f32_e32 v46, v144, v46
	v_mul_f32_e32 v47, v144, v47
	v_mul_f32_e32 v44, v144, v44
	v_mul_f32_e32 v45, v144, v45
	v_mul_f32_e32 v42, v144, v42
	v_mul_f32_e32 v43, v144, v43
	v_mul_f32_e32 v40, v144, v40
	v_mul_f32_e32 v41, v144, v41
	v_mul_f32_e32 v38, v144, v38
	v_mul_f32_e32 v39, v144, v39
	v_mul_f32_e32 v36, v144, v36
	v_mul_f32_e32 v37, v144, v37
	v_mul_f32_e32 v34, v144, v34
	v_mul_f32_e32 v35, v144, v35
	v_mul_f32_e32 v32, v144, v32
	v_mul_f32_e32 v33, v144, v33
	v_mul_f32_e32 v14, v144, v14
	v_mul_f32_e32 v15, v144, v15
	v_mul_f32_e32 v12, v144, v12
	v_mul_f32_e32 v13, v144, v13
	v_mul_f32_e32 v10, v144, v10
	v_mul_f32_e32 v11, v144, v11
	v_mul_f32_e32 v8, v144, v8
	v_mul_f32_e32 v9, v144, v9
	v_mul_f32_e32 v6, v144, v6
	v_mul_f32_e32 v7, v144, v7
	v_mul_f32_e32 v4, v144, v4
	v_mul_f32_e32 v5, v144, v5
	v_mul_f32_e32 v2, v144, v2
	v_mul_f32_e32 v3, v144, v3
	v_mul_f32_e32 v0, v144, v0
	v_mul_f32_e32 v1, v144, v1
.LBB0_900:
	v_sub_f32_e32 v145, v174, v204
	v_sub_f32_e32 v146, v174, v205
	v_sub_f32_e32 v112, v112, v145
	v_sub_f32_e32 v96, v96, v146
	v_exp_f32_e32 v112, v112
	v_exp_f32_e32 v96, v96
	v_sub_f32_e32 v113, v113, v145
	v_sub_f32_e32 v97, v97, v146
	v_exp_f32_e32 v113, v113
	v_exp_f32_e32 v97, v97
	v_sub_f32_e32 v114, v114, v145
	v_sub_f32_e32 v98, v98, v146
	v_exp_f32_e32 v114, v114
	v_exp_f32_e32 v98, v98
	v_sub_f32_e32 v115, v115, v145
	v_sub_f32_e32 v99, v99, v146
	v_exp_f32_e32 v115, v115
	v_exp_f32_e32 v99, v99
	v_sub_f32_e32 v116, v116, v145
	v_sub_f32_e32 v100, v100, v146
	v_exp_f32_e32 v116, v116
	v_exp_f32_e32 v100, v100
	v_sub_f32_e32 v117, v117, v145
	v_sub_f32_e32 v101, v101, v146
	v_add_f32_e32 v147, v113, v112
	v_add_f32_e32 v148, v97, v96
	v_exp_f32_e32 v117, v117
	v_exp_f32_e32 v101, v101
	v_sub_f32_e32 v118, v118, v145
	v_sub_f32_e32 v102, v102, v146
	v_add_f32_e32 v147, v114, v147
	v_add_f32_e32 v148, v98, v148
	v_exp_f32_e32 v118, v118
	v_exp_f32_e32 v102, v102
	v_sub_f32_e32 v119, v119, v145
	v_sub_f32_e32 v103, v103, v146
	v_add_f32_e32 v147, v115, v147
	v_add_f32_e32 v148, v99, v148
	v_exp_f32_e32 v119, v119
	v_exp_f32_e32 v103, v103
	v_sub_f32_e32 v120, v120, v145
	v_sub_f32_e32 v104, v104, v146
	v_add_f32_e32 v147, v116, v147
	v_add_f32_e32 v148, v100, v148
	v_exp_f32_e32 v120, v120
	v_exp_f32_e32 v104, v104
	v_sub_f32_e32 v121, v121, v145
	v_sub_f32_e32 v105, v105, v146
	v_add_f32_e32 v147, v117, v147
	v_add_f32_e32 v148, v101, v148
	v_exp_f32_e32 v121, v121
	v_exp_f32_e32 v105, v105
	v_sub_f32_e32 v122, v122, v145
	v_sub_f32_e32 v106, v106, v146
	v_add_f32_e32 v147, v118, v147
	v_add_f32_e32 v148, v102, v148
	v_exp_f32_e32 v122, v122
	v_exp_f32_e32 v106, v106
	v_sub_f32_e32 v123, v123, v145
	v_sub_f32_e32 v107, v107, v146
	v_add_f32_e32 v147, v119, v147
	v_add_f32_e32 v148, v103, v148
	v_exp_f32_e32 v123, v123
	v_exp_f32_e32 v107, v107
	v_sub_f32_e32 v124, v124, v145
	v_sub_f32_e32 v108, v108, v146
	v_add_f32_e32 v147, v120, v147
	v_add_f32_e32 v148, v104, v148
	v_exp_f32_e32 v124, v124
	v_exp_f32_e32 v108, v108
	v_sub_f32_e32 v125, v125, v145
	v_sub_f32_e32 v109, v109, v146
	v_add_f32_e32 v147, v121, v147
	v_add_f32_e32 v148, v105, v148
	v_exp_f32_e32 v125, v125
	v_exp_f32_e32 v109, v109
	v_sub_f32_e32 v126, v126, v145
	v_sub_f32_e32 v110, v110, v146
	v_add_f32_e32 v147, v122, v147
	v_add_f32_e32 v148, v106, v148
	v_exp_f32_e32 v126, v126
	v_exp_f32_e32 v110, v110
	v_sub_f32_e32 v127, v127, v145
	v_sub_f32_e32 v111, v111, v146
	v_add_f32_e32 v147, v123, v147
	v_add_f32_e32 v148, v107, v148
	v_exp_f32_e32 v127, v127
	v_exp_f32_e32 v111, v111
	v_add_f32_e32 v147, v124, v147
	v_add_f32_e32 v148, v108, v148
	v_add_f32_e32 v147, v125, v147
	v_add_f32_e32 v148, v109, v148
	v_add_f32_e32 v145, v126, v147
	v_add_f32_e32 v146, v110, v148
	v_add_f32_e32 v145, v127, v145
	v_add_f32_e32 v146, v111, v146
	v_add_f32_e32 v179, v145, v146
	v_fma_f32 v193, v193, v144, v179
	v_cvt_pk_bf16_f32 v144, v112, v113
	v_cvt_pk_bf16_f32 v145, v114, v115
	v_cvt_pk_bf16_f32 v146, v116, v117
	v_cvt_pk_bf16_f32 v147, v118, v119
	v_cvt_pk_bf16_f32 v148, v120, v121
	v_cvt_pk_bf16_f32 v149, v122, v123
	v_cvt_pk_bf16_f32 v150, v124, v125
	v_cvt_pk_bf16_f32 v151, v126, v127
	v_cvt_pk_bf16_f32 v152, v96, v97
	v_cvt_pk_bf16_f32 v153, v98, v99
	v_cvt_pk_bf16_f32 v154, v100, v101
	v_cvt_pk_bf16_f32 v155, v102, v103
	v_cvt_pk_bf16_f32 v156, v104, v105
	v_cvt_pk_bf16_f32 v157, v106, v107
	v_cvt_pk_bf16_f32 v158, v108, v109
	v_cvt_pk_bf16_f32 v159, v110, v111
	s_xor_b64 s[80:81], s[80:81], -1
	s_andn2_b64 vcc, exec, s[82:83]
	s_cbranch_vccz .LBB0_902
	s_branch .LBB0_903

.LBB0_911:
	v_max_f32_e32 v96, v80, v81
	v_max_f32_e32 v99, v64, v65
	v_max3_f32 v96, v96, v82, v83
	v_max3_f32 v99, v99, v66, v67
	v_max3_f32 v96, v96, v84, v85
	v_max3_f32 v99, v99, v68, v69
	v_max3_f32 v96, v96, v86, v87
	v_max3_f32 v99, v99, v70, v71
	v_max3_f32 v96, v96, v88, v89
	v_max3_f32 v99, v99, v72, v73
	v_max3_f32 v96, v96, v90, v91
	v_max3_f32 v99, v99, v74, v75
	v_max3_f32 v96, v96, v92, v93
	v_max3_f32 v99, v99, v76, v77
	v_max3_f32 v96, v96, v94, v95
	v_max3_f32 v99, v99, v78, v79
	v_add_f32_e32 v96, v97, v96
	v_add_f32_e32 v99, v98, v99
	v_max_f32_e32 v96, v96, v99
	v_mov_b32_e32 v99, v96
	s_nop 1
	v_permlane32_swap_b32_e32 v96, v99
	v_max_f32_e32 v96, v96, v99
	v_sub_f32_e32 v99, v96, v174
	v_cmp_gt_f32_e32 vcc, s18, v99
	s_cmp_lg_u64 vcc, exec
	s_cselect_b64 s[78:79], -1, 0
	s_cmp_eq_u64 vcc, exec
	s_cbranch_scc1 .LBB0_915
	v_max_f32_e32 v203, v174, v96
	v_sub_f32_e32 v96, v174, v203
	v_exp_f32_e32 v96, v96
	s_nop 0
	v_cmp_neq_f32_e32 vcc, 1.0, v96
	s_cbranch_vccz .LBB0_914
	v_mul_f32_e32 v30, v96, v30
	v_mul_f32_e32 v31, v96, v31
	v_mul_f32_e32 v28, v96, v28
	v_mul_f32_e32 v29, v96, v29
	v_mul_f32_e32 v26, v96, v26
	v_mul_f32_e32 v27, v96, v27
	v_mul_f32_e32 v24, v96, v24
	v_mul_f32_e32 v25, v96, v25
	v_mul_f32_e32 v22, v96, v22
	v_mul_f32_e32 v23, v96, v23
	v_mul_f32_e32 v20, v96, v20
	v_mul_f32_e32 v21, v96, v21
	v_mul_f32_e32 v18, v96, v18
	v_mul_f32_e32 v19, v96, v19
	v_mul_f32_e32 v16, v96, v16
	v_mul_f32_e32 v17, v96, v17
	v_mul_f32_e32 v62, v96, v62
	v_mul_f32_e32 v63, v96, v63
	v_mul_f32_e32 v60, v96, v60
	v_mul_f32_e32 v61, v96, v61
	v_mul_f32_e32 v58, v96, v58
	v_mul_f32_e32 v59, v96, v59
	v_mul_f32_e32 v56, v96, v56
	v_mul_f32_e32 v57, v96, v57
	v_mul_f32_e32 v54, v96, v54
	v_mul_f32_e32 v55, v96, v55
	v_mul_f32_e32 v52, v96, v52
	v_mul_f32_e32 v53, v96, v53
	v_mul_f32_e32 v50, v96, v50
	v_mul_f32_e32 v51, v96, v51
	v_mul_f32_e32 v48, v96, v48
	v_mul_f32_e32 v49, v96, v49
	v_mul_f32_e32 v46, v96, v46
	v_mul_f32_e32 v47, v96, v47
	v_mul_f32_e32 v44, v96, v44
	v_mul_f32_e32 v45, v96, v45
	v_mul_f32_e32 v42, v96, v42
	v_mul_f32_e32 v43, v96, v43
	v_mul_f32_e32 v40, v96, v40
	v_mul_f32_e32 v41, v96, v41
	v_mul_f32_e32 v38, v96, v38
	v_mul_f32_e32 v39, v96, v39
	v_mul_f32_e32 v36, v96, v36
	v_mul_f32_e32 v37, v96, v37
	v_mul_f32_e32 v34, v96, v34
	v_mul_f32_e32 v35, v96, v35
	v_mul_f32_e32 v32, v96, v32
	v_mul_f32_e32 v33, v96, v33
	v_mul_f32_e32 v14, v96, v14
	v_mul_f32_e32 v15, v96, v15
	v_mul_f32_e32 v12, v96, v12
	v_mul_f32_e32 v13, v96, v13
	v_mul_f32_e32 v10, v96, v10
	v_mul_f32_e32 v11, v96, v11
	v_mul_f32_e32 v8, v96, v8
	v_mul_f32_e32 v9, v96, v9
	v_mul_f32_e32 v6, v96, v6
	v_mul_f32_e32 v7, v96, v7
	v_mul_f32_e32 v4, v96, v4
	v_mul_f32_e32 v5, v96, v5
	v_mul_f32_e32 v2, v96, v2
	v_mul_f32_e32 v3, v96, v3
	v_mul_f32_e32 v0, v96, v0
	v_mul_f32_e32 v1, v96, v1
.LBB0_914:
	v_sub_f32_e32 v97, v203, v97
	v_sub_f32_e32 v98, v203, v98
	v_sub_f32_e32 v80, v80, v97
	v_sub_f32_e32 v64, v64, v98
	v_exp_f32_e32 v80, v80
	v_exp_f32_e32 v64, v64
	v_sub_f32_e32 v81, v81, v97
	v_sub_f32_e32 v65, v65, v98
	v_exp_f32_e32 v81, v81
	v_exp_f32_e32 v65, v65
	v_sub_f32_e32 v82, v82, v97
	v_sub_f32_e32 v66, v66, v98
	v_exp_f32_e32 v82, v82
	v_exp_f32_e32 v66, v66
	v_sub_f32_e32 v83, v83, v97
	v_sub_f32_e32 v67, v67, v98
	v_exp_f32_e32 v83, v83
	v_exp_f32_e32 v67, v67
	v_sub_f32_e32 v84, v84, v97
	v_sub_f32_e32 v68, v68, v98
	v_exp_f32_e32 v84, v84
	v_exp_f32_e32 v68, v68
	v_sub_f32_e32 v85, v85, v97
	v_sub_f32_e32 v69, v69, v98
	v_add_f32_e32 v99, v81, v80
	v_add_f32_e32 v100, v65, v64
	v_exp_f32_e32 v85, v85
	v_exp_f32_e32 v69, v69
	v_sub_f32_e32 v86, v86, v97
	v_sub_f32_e32 v70, v70, v98
	v_add_f32_e32 v99, v82, v99
	v_add_f32_e32 v100, v66, v100
	v_exp_f32_e32 v86, v86
	v_exp_f32_e32 v70, v70
	v_sub_f32_e32 v87, v87, v97
	v_sub_f32_e32 v71, v71, v98
	v_add_f32_e32 v99, v83, v99
	v_add_f32_e32 v100, v67, v100
	v_exp_f32_e32 v87, v87
	v_exp_f32_e32 v71, v71
	v_sub_f32_e32 v88, v88, v97
	v_sub_f32_e32 v72, v72, v98
	v_add_f32_e32 v99, v84, v99
	v_add_f32_e32 v100, v68, v100
	v_exp_f32_e32 v88, v88
	v_exp_f32_e32 v72, v72
	v_sub_f32_e32 v89, v89, v97
	v_sub_f32_e32 v73, v73, v98
	v_add_f32_e32 v99, v85, v99
	v_add_f32_e32 v100, v69, v100
	v_exp_f32_e32 v89, v89
	v_exp_f32_e32 v73, v73
	v_sub_f32_e32 v90, v90, v97
	v_sub_f32_e32 v74, v74, v98
	v_add_f32_e32 v99, v86, v99
	v_add_f32_e32 v100, v70, v100
	v_exp_f32_e32 v90, v90
	v_exp_f32_e32 v74, v74
	v_sub_f32_e32 v91, v91, v97
	v_sub_f32_e32 v75, v75, v98
	v_add_f32_e32 v99, v87, v99
	v_add_f32_e32 v100, v71, v100
	v_exp_f32_e32 v91, v91
	v_exp_f32_e32 v75, v75
	v_sub_f32_e32 v92, v92, v97
	v_sub_f32_e32 v76, v76, v98
	v_add_f32_e32 v99, v88, v99
	v_add_f32_e32 v100, v72, v100
	v_exp_f32_e32 v92, v92
	v_exp_f32_e32 v76, v76
	v_sub_f32_e32 v93, v93, v97
	v_sub_f32_e32 v77, v77, v98
	v_add_f32_e32 v99, v89, v99
	v_add_f32_e32 v100, v73, v100
	v_exp_f32_e32 v93, v93
	v_exp_f32_e32 v77, v77
	v_sub_f32_e32 v94, v94, v97
	v_sub_f32_e32 v78, v78, v98
	v_add_f32_e32 v99, v90, v99
	v_add_f32_e32 v100, v74, v100
	v_exp_f32_e32 v94, v94
	v_exp_f32_e32 v78, v78
	v_sub_f32_e32 v95, v95, v97
	v_sub_f32_e32 v79, v79, v98
	v_add_f32_e32 v99, v91, v99
	v_add_f32_e32 v100, v75, v100
	v_exp_f32_e32 v95, v95
	v_exp_f32_e32 v79, v79
	v_add_f32_e32 v99, v92, v99
	v_add_f32_e32 v100, v76, v100
	v_add_f32_e32 v99, v93, v99
	v_add_f32_e32 v100, v77, v100
	v_add_f32_e32 v97, v94, v99
	v_add_f32_e32 v98, v78, v100
	v_add_f32_e32 v97, v95, v97
	v_add_f32_e32 v98, v79, v98
	v_add_f32_e32 v97, v97, v98
	v_fma_f32 v193, v193, v96, v97
	v_cvt_pk_bf16_f32 v144, v80, v81
	v_cvt_pk_bf16_f32 v145, v82, v83
	v_cvt_pk_bf16_f32 v146, v84, v85
	v_cvt_pk_bf16_f32 v147, v86, v87
	v_cvt_pk_bf16_f32 v148, v88, v89
	v_cvt_pk_bf16_f32 v149, v90, v91
	v_cvt_pk_bf16_f32 v150, v92, v93
	v_cvt_pk_bf16_f32 v151, v94, v95
	v_cvt_pk_bf16_f32 v152, v64, v65
	v_cvt_pk_bf16_f32 v153, v66, v67
	v_cvt_pk_bf16_f32 v154, v68, v69
	v_cvt_pk_bf16_f32 v155, v70, v71
	v_cvt_pk_bf16_f32 v156, v72, v73
	v_cvt_pk_bf16_f32 v157, v74, v75
	v_cvt_pk_bf16_f32 v158, v76, v77
	v_cvt_pk_bf16_f32 v159, v78, v79
	s_andn2_b64 vcc, exec, s[78:79]
	s_cbranch_vccnz .LBB0_883
	s_branch .LBB0_916

.LBB0_930:
	v_max_f32_e32 v128, v112, v113
	v_max_f32_e32 v129, v96, v97
	v_max3_f32 v128, v128, v114, v115
	v_max3_f32 v129, v129, v98, v99
	v_max3_f32 v128, v128, v116, v117
	v_max3_f32 v129, v129, v100, v101
	v_max3_f32 v128, v128, v118, v119
	v_max3_f32 v129, v129, v102, v103
	v_max3_f32 v128, v128, v120, v121
	v_max3_f32 v129, v129, v104, v105
	v_max3_f32 v128, v128, v122, v123
	v_max3_f32 v129, v129, v106, v107
	v_max3_f32 v128, v128, v124, v125
	v_max3_f32 v129, v129, v108, v109
	v_max3_f32 v128, v128, v126, v127
	v_max3_f32 v129, v129, v110, v111
	v_add_f32_e32 v128, v130, v128
	v_add_f32_e32 v129, v131, v129
	v_max_f32_e32 v128, v128, v129
	v_mov_b32_e32 v129, v128
	s_nop 1
	v_permlane32_swap_b32_e32 v128, v129
	v_max_f32_e32 v128, v128, v129
	v_sub_f32_e32 v129, v128, v203
	v_cmp_gt_f32_e32 vcc, s18, v129
	s_cmp_lg_u64 vcc, exec
	s_cselect_b64 s[82:83], -1, 0
	s_cmp_eq_u64 vcc, exec
	s_cbranch_scc1 .LBB0_934
	v_max_f32_e32 v129, v203, v128
	v_sub_f32_e32 v128, v203, v129
	v_exp_f32_e32 v128, v128
	s_nop 0
	v_cmp_neq_f32_e32 vcc, 1.0, v128
	s_cbranch_vccz .LBB0_933
	v_mul_f32_e32 v30, v128, v30
	v_mul_f32_e32 v31, v128, v31
	v_mul_f32_e32 v28, v128, v28
	v_mul_f32_e32 v29, v128, v29
	v_mul_f32_e32 v26, v128, v26
	v_mul_f32_e32 v27, v128, v27
	v_mul_f32_e32 v24, v128, v24
	v_mul_f32_e32 v25, v128, v25
	v_mul_f32_e32 v22, v128, v22
	v_mul_f32_e32 v23, v128, v23
	v_mul_f32_e32 v20, v128, v20
	v_mul_f32_e32 v21, v128, v21
	v_mul_f32_e32 v18, v128, v18
	v_mul_f32_e32 v19, v128, v19
	v_mul_f32_e32 v16, v128, v16
	v_mul_f32_e32 v17, v128, v17
	v_mul_f32_e32 v62, v128, v62
	v_mul_f32_e32 v63, v128, v63
	v_mul_f32_e32 v60, v128, v60
	v_mul_f32_e32 v61, v128, v61
	v_mul_f32_e32 v58, v128, v58
	v_mul_f32_e32 v59, v128, v59
	v_mul_f32_e32 v56, v128, v56
	v_mul_f32_e32 v57, v128, v57
	v_mul_f32_e32 v54, v128, v54
	v_mul_f32_e32 v55, v128, v55
	v_mul_f32_e32 v52, v128, v52
	v_mul_f32_e32 v53, v128, v53
	v_mul_f32_e32 v50, v128, v50
	v_mul_f32_e32 v51, v128, v51
	v_mul_f32_e32 v48, v128, v48
	v_mul_f32_e32 v49, v128, v49
	v_mul_f32_e32 v46, v128, v46
	v_mul_f32_e32 v47, v128, v47
	v_mul_f32_e32 v44, v128, v44
	v_mul_f32_e32 v45, v128, v45
	v_mul_f32_e32 v42, v128, v42
	v_mul_f32_e32 v43, v128, v43
	v_mul_f32_e32 v40, v128, v40
	v_mul_f32_e32 v41, v128, v41
	v_mul_f32_e32 v38, v128, v38
	v_mul_f32_e32 v39, v128, v39
	v_mul_f32_e32 v36, v128, v36
	v_mul_f32_e32 v37, v128, v37
	v_mul_f32_e32 v34, v128, v34
	v_mul_f32_e32 v35, v128, v35
	v_mul_f32_e32 v32, v128, v32
	v_mul_f32_e32 v33, v128, v33
	v_mul_f32_e32 v14, v128, v14
	v_mul_f32_e32 v15, v128, v15
	v_mul_f32_e32 v12, v128, v12
	v_mul_f32_e32 v13, v128, v13
	v_mul_f32_e32 v10, v128, v10
	v_mul_f32_e32 v11, v128, v11
	v_mul_f32_e32 v8, v128, v8
	v_mul_f32_e32 v9, v128, v9
	v_mul_f32_e32 v6, v128, v6
	v_mul_f32_e32 v7, v128, v7
	v_mul_f32_e32 v4, v128, v4
	v_mul_f32_e32 v5, v128, v5
	v_mul_f32_e32 v2, v128, v2
	v_mul_f32_e32 v3, v128, v3
	v_mul_f32_e32 v0, v128, v0
	v_mul_f32_e32 v1, v128, v1
.LBB0_933:
	v_sub_f32_e32 v130, v129, v130
	v_sub_f32_e32 v131, v129, v131
	v_sub_f32_e32 v112, v112, v130
	v_sub_f32_e32 v96, v96, v131
	v_exp_f32_e32 v112, v112
	v_exp_f32_e32 v96, v96
	v_sub_f32_e32 v113, v113, v130
	v_sub_f32_e32 v97, v97, v131
	v_exp_f32_e32 v113, v113
	v_exp_f32_e32 v97, v97
	v_sub_f32_e32 v114, v114, v130
	v_sub_f32_e32 v98, v98, v131
	v_exp_f32_e32 v114, v114
	v_exp_f32_e32 v98, v98
	v_sub_f32_e32 v115, v115, v130
	v_sub_f32_e32 v99, v99, v131
	v_exp_f32_e32 v115, v115
	v_exp_f32_e32 v99, v99
	v_sub_f32_e32 v116, v116, v130
	v_sub_f32_e32 v100, v100, v131
	v_exp_f32_e32 v116, v116
	v_exp_f32_e32 v100, v100
	v_sub_f32_e32 v117, v117, v130
	v_sub_f32_e32 v101, v101, v131
	v_add_f32_e32 v132, v113, v112
	v_add_f32_e32 v133, v97, v96
	v_exp_f32_e32 v117, v117
	v_exp_f32_e32 v101, v101
	v_sub_f32_e32 v118, v118, v130
	v_sub_f32_e32 v102, v102, v131
	v_add_f32_e32 v132, v114, v132
	v_add_f32_e32 v133, v98, v133
	v_exp_f32_e32 v118, v118
	v_exp_f32_e32 v102, v102
	v_sub_f32_e32 v119, v119, v130
	v_sub_f32_e32 v103, v103, v131
	v_add_f32_e32 v132, v115, v132
	v_add_f32_e32 v133, v99, v133
	v_exp_f32_e32 v119, v119
	v_exp_f32_e32 v103, v103
	v_sub_f32_e32 v120, v120, v130
	v_sub_f32_e32 v104, v104, v131
	v_add_f32_e32 v132, v116, v132
	v_add_f32_e32 v133, v100, v133
	v_exp_f32_e32 v120, v120
	v_exp_f32_e32 v104, v104
	v_sub_f32_e32 v121, v121, v130
	v_sub_f32_e32 v105, v105, v131
	v_add_f32_e32 v132, v117, v132
	v_add_f32_e32 v133, v101, v133
	v_exp_f32_e32 v121, v121
	v_exp_f32_e32 v105, v105
	v_sub_f32_e32 v122, v122, v130
	v_sub_f32_e32 v106, v106, v131
	v_add_f32_e32 v132, v118, v132
	v_add_f32_e32 v133, v102, v133
	v_exp_f32_e32 v122, v122
	v_exp_f32_e32 v106, v106
	v_sub_f32_e32 v123, v123, v130
	v_sub_f32_e32 v107, v107, v131
	v_add_f32_e32 v132, v119, v132
	v_add_f32_e32 v133, v103, v133
	v_exp_f32_e32 v123, v123
	v_exp_f32_e32 v107, v107
	v_sub_f32_e32 v124, v124, v130
	v_sub_f32_e32 v108, v108, v131
	v_add_f32_e32 v132, v120, v132
	v_add_f32_e32 v133, v104, v133
	v_exp_f32_e32 v124, v124
	v_exp_f32_e32 v108, v108
	v_sub_f32_e32 v125, v125, v130
	v_sub_f32_e32 v109, v109, v131
	v_add_f32_e32 v132, v121, v132
	v_add_f32_e32 v133, v105, v133
	v_exp_f32_e32 v125, v125
	v_exp_f32_e32 v109, v109
	v_sub_f32_e32 v126, v126, v130
	v_sub_f32_e32 v110, v110, v131
	v_add_f32_e32 v132, v122, v132
	v_add_f32_e32 v133, v106, v133
	v_exp_f32_e32 v126, v126
	v_exp_f32_e32 v110, v110
	v_sub_f32_e32 v127, v127, v130
	v_sub_f32_e32 v111, v111, v131
	v_add_f32_e32 v132, v123, v132
	v_add_f32_e32 v133, v107, v133
	v_exp_f32_e32 v127, v127
	v_exp_f32_e32 v111, v111
	v_add_f32_e32 v132, v124, v132
	v_add_f32_e32 v133, v108, v133
	v_add_f32_e32 v132, v125, v132
	v_add_f32_e32 v133, v109, v133
	v_add_f32_e32 v130, v126, v132
	v_add_f32_e32 v131, v110, v133
	v_add_f32_e32 v130, v127, v130
	v_add_f32_e32 v131, v111, v131
	v_add_f32_e32 v130, v130, v131
	v_fma_f32 v193, v193, v128, v130
	v_cvt_pk_bf16_f32 v144, v112, v113
	v_cvt_pk_bf16_f32 v145, v114, v115
	v_cvt_pk_bf16_f32 v146, v116, v117
	v_cvt_pk_bf16_f32 v147, v118, v119
	v_cvt_pk_bf16_f32 v148, v120, v121
	v_cvt_pk_bf16_f32 v149, v122, v123
	v_cvt_pk_bf16_f32 v150, v124, v125
	v_cvt_pk_bf16_f32 v151, v126, v127
	v_cvt_pk_bf16_f32 v152, v96, v97
	v_cvt_pk_bf16_f32 v153, v98, v99
	v_cvt_pk_bf16_f32 v154, v100, v101
	v_cvt_pk_bf16_f32 v155, v102, v103
	v_cvt_pk_bf16_f32 v156, v104, v105
	v_cvt_pk_bf16_f32 v157, v106, v107
	v_cvt_pk_bf16_f32 v158, v108, v109
	v_cvt_pk_bf16_f32 v159, v110, v111
	s_xor_b64 s[80:81], s[80:81], -1
	s_andn2_b64 vcc, exec, s[82:83]
	s_cbranch_vccz .LBB0_935
	s_branch .LBB0_936

.LBB0_944:
	v_max_f32_e32 v96, v80, v81
	v_max_f32_e32 v99, v64, v65
	v_max3_f32 v96, v96, v82, v83
	v_max3_f32 v99, v99, v66, v67
	v_max3_f32 v96, v96, v84, v85
	v_max3_f32 v99, v99, v68, v69
	v_max3_f32 v96, v96, v86, v87
	v_max3_f32 v99, v99, v70, v71
	v_max3_f32 v96, v96, v88, v89
	v_max3_f32 v99, v99, v72, v73
	v_max3_f32 v96, v96, v90, v91
	v_max3_f32 v99, v99, v74, v75
	v_max3_f32 v96, v96, v92, v93
	v_max3_f32 v99, v99, v76, v77
	v_max3_f32 v96, v96, v94, v95
	v_max3_f32 v99, v99, v78, v79
	v_add_f32_e32 v96, v97, v96
	v_add_f32_e32 v99, v98, v99
	v_max_f32_e32 v96, v96, v99
	v_mov_b32_e32 v99, v96
	s_nop 1
	v_permlane32_swap_b32_e32 v96, v99
	v_max_f32_e32 v96, v96, v99
	v_sub_f32_e32 v99, v96, v129
	v_cmp_gt_f32_e32 vcc, s18, v99
	v_readlane_b32 s48, v255, 6
	s_cmp_lg_u64 vcc, exec
	v_readlane_b32 s49, v255, 7
	v_readlane_b32 s50, v255, 8
	v_readlane_b32 s51, v255, 9
	s_cselect_b64 s[76:77], -1, 0
	s_cmp_eq_u64 vcc, exec
	s_cbranch_scc1 .LBB0_948
	v_max_f32_e32 v99, v129, v96
	v_sub_f32_e32 v96, v129, v99
	v_exp_f32_e32 v96, v96
	s_nop 0
	v_cmp_neq_f32_e32 vcc, 1.0, v96
	s_cbranch_vccz .LBB0_947
	v_mul_f32_e32 v30, v96, v30
	v_mul_f32_e32 v31, v96, v31
	v_mul_f32_e32 v28, v96, v28
	v_mul_f32_e32 v29, v96, v29
	v_mul_f32_e32 v26, v96, v26
	v_mul_f32_e32 v27, v96, v27
	v_mul_f32_e32 v24, v96, v24
	v_mul_f32_e32 v25, v96, v25
	v_mul_f32_e32 v22, v96, v22
	v_mul_f32_e32 v23, v96, v23
	v_mul_f32_e32 v20, v96, v20
	v_mul_f32_e32 v21, v96, v21
	v_mul_f32_e32 v18, v96, v18
	v_mul_f32_e32 v19, v96, v19
	v_mul_f32_e32 v16, v96, v16
	v_mul_f32_e32 v17, v96, v17
	v_mul_f32_e32 v62, v96, v62
	v_mul_f32_e32 v63, v96, v63
	v_mul_f32_e32 v60, v96, v60
	v_mul_f32_e32 v61, v96, v61
	v_mul_f32_e32 v58, v96, v58
	v_mul_f32_e32 v59, v96, v59
	v_mul_f32_e32 v56, v96, v56
	v_mul_f32_e32 v57, v96, v57
	v_mul_f32_e32 v54, v96, v54
	v_mul_f32_e32 v55, v96, v55
	v_mul_f32_e32 v52, v96, v52
	v_mul_f32_e32 v53, v96, v53
	v_mul_f32_e32 v50, v96, v50
	v_mul_f32_e32 v51, v96, v51
	v_mul_f32_e32 v48, v96, v48
	v_mul_f32_e32 v49, v96, v49
	v_mul_f32_e32 v46, v96, v46
	v_mul_f32_e32 v47, v96, v47
	v_mul_f32_e32 v44, v96, v44
	v_mul_f32_e32 v45, v96, v45
	v_mul_f32_e32 v42, v96, v42
	v_mul_f32_e32 v43, v96, v43
	v_mul_f32_e32 v40, v96, v40
	v_mul_f32_e32 v41, v96, v41
	v_mul_f32_e32 v38, v96, v38
	v_mul_f32_e32 v39, v96, v39
	v_mul_f32_e32 v36, v96, v36
	v_mul_f32_e32 v37, v96, v37
	v_mul_f32_e32 v34, v96, v34
	v_mul_f32_e32 v35, v96, v35
	v_mul_f32_e32 v32, v96, v32
	v_mul_f32_e32 v33, v96, v33
	v_mul_f32_e32 v14, v96, v14
	v_mul_f32_e32 v15, v96, v15
	v_mul_f32_e32 v12, v96, v12
	v_mul_f32_e32 v13, v96, v13
	v_mul_f32_e32 v10, v96, v10
	v_mul_f32_e32 v11, v96, v11
	v_mul_f32_e32 v8, v96, v8
	v_mul_f32_e32 v9, v96, v9
	v_mul_f32_e32 v6, v96, v6
	v_mul_f32_e32 v7, v96, v7
	v_mul_f32_e32 v4, v96, v4
	v_mul_f32_e32 v5, v96, v5
	v_mul_f32_e32 v2, v96, v2
	v_mul_f32_e32 v3, v96, v3
	v_mul_f32_e32 v0, v96, v0
	v_mul_f32_e32 v1, v96, v1
.LBB0_947:
	v_sub_f32_e32 v97, v99, v97
	v_sub_f32_e32 v98, v99, v98
	v_sub_f32_e32 v80, v80, v97
	v_sub_f32_e32 v64, v64, v98
	v_exp_f32_e32 v80, v80
	v_exp_f32_e32 v64, v64
	v_sub_f32_e32 v81, v81, v97
	v_sub_f32_e32 v65, v65, v98
	v_exp_f32_e32 v81, v81
	v_exp_f32_e32 v65, v65
	v_sub_f32_e32 v82, v82, v97
	v_sub_f32_e32 v66, v66, v98
	v_exp_f32_e32 v82, v82
	v_exp_f32_e32 v66, v66
	v_sub_f32_e32 v83, v83, v97
	v_sub_f32_e32 v67, v67, v98
	v_exp_f32_e32 v83, v83
	v_exp_f32_e32 v67, v67
	v_sub_f32_e32 v84, v84, v97
	v_sub_f32_e32 v68, v68, v98
	v_exp_f32_e32 v84, v84
	v_exp_f32_e32 v68, v68
	v_sub_f32_e32 v85, v85, v97
	v_sub_f32_e32 v69, v69, v98
	v_add_f32_e32 v99, v81, v80
	v_add_f32_e32 v100, v65, v64
	v_exp_f32_e32 v85, v85
	v_exp_f32_e32 v69, v69
	v_sub_f32_e32 v86, v86, v97
	v_sub_f32_e32 v70, v70, v98
	v_add_f32_e32 v99, v82, v99
	v_add_f32_e32 v100, v66, v100
	v_exp_f32_e32 v86, v86
	v_exp_f32_e32 v70, v70
	v_sub_f32_e32 v87, v87, v97
	v_sub_f32_e32 v71, v71, v98
	v_add_f32_e32 v99, v83, v99
	v_add_f32_e32 v100, v67, v100
	v_exp_f32_e32 v87, v87
	v_exp_f32_e32 v71, v71
	v_sub_f32_e32 v88, v88, v97
	v_sub_f32_e32 v72, v72, v98
	v_add_f32_e32 v99, v84, v99
	v_add_f32_e32 v100, v68, v100
	v_exp_f32_e32 v88, v88
	v_exp_f32_e32 v72, v72
	v_sub_f32_e32 v89, v89, v97
	v_sub_f32_e32 v73, v73, v98
	v_add_f32_e32 v99, v85, v99
	v_add_f32_e32 v100, v69, v100
	v_exp_f32_e32 v89, v89
	v_exp_f32_e32 v73, v73
	v_sub_f32_e32 v90, v90, v97
	v_sub_f32_e32 v74, v74, v98
	v_add_f32_e32 v99, v86, v99
	v_add_f32_e32 v100, v70, v100
	v_exp_f32_e32 v90, v90
	v_exp_f32_e32 v74, v74
	v_sub_f32_e32 v91, v91, v97
	v_sub_f32_e32 v75, v75, v98
	v_add_f32_e32 v99, v87, v99
	v_add_f32_e32 v100, v71, v100
	v_exp_f32_e32 v91, v91
	v_exp_f32_e32 v75, v75
	v_sub_f32_e32 v92, v92, v97
	v_sub_f32_e32 v76, v76, v98
	v_add_f32_e32 v99, v88, v99
	v_add_f32_e32 v100, v72, v100
	v_exp_f32_e32 v92, v92
	v_exp_f32_e32 v76, v76
	v_sub_f32_e32 v93, v93, v97
	v_sub_f32_e32 v77, v77, v98
	v_add_f32_e32 v99, v89, v99
	v_add_f32_e32 v100, v73, v100
	v_exp_f32_e32 v93, v93
	v_exp_f32_e32 v77, v77
	v_sub_f32_e32 v94, v94, v97
	v_sub_f32_e32 v78, v78, v98
	v_add_f32_e32 v99, v90, v99
	v_add_f32_e32 v100, v74, v100
	v_exp_f32_e32 v94, v94
	v_exp_f32_e32 v78, v78
	v_sub_f32_e32 v95, v95, v97
	v_sub_f32_e32 v79, v79, v98
	v_add_f32_e32 v99, v91, v99
	v_add_f32_e32 v100, v75, v100
	v_exp_f32_e32 v95, v95
	v_exp_f32_e32 v79, v79
	v_add_f32_e32 v99, v92, v99
	v_add_f32_e32 v100, v76, v100
	v_add_f32_e32 v99, v93, v99
	v_add_f32_e32 v100, v77, v100
	v_add_f32_e32 v97, v94, v99
	v_add_f32_e32 v98, v78, v100
	v_add_f32_e32 v97, v95, v97
	v_add_f32_e32 v98, v79, v98
	v_add_f32_e32 v97, v97, v98
	v_fmac_f32_e32 v97, v193, v96
	v_cvt_pk_bf16_f32 v144, v80, v81
	v_cvt_pk_bf16_f32 v145, v82, v83
	v_cvt_pk_bf16_f32 v146, v84, v85
	v_cvt_pk_bf16_f32 v147, v86, v87
	v_cvt_pk_bf16_f32 v148, v88, v89
	v_cvt_pk_bf16_f32 v149, v90, v91
	v_cvt_pk_bf16_f32 v150, v92, v93
	v_cvt_pk_bf16_f32 v151, v94, v95
	v_cvt_pk_bf16_f32 v152, v64, v65
	v_cvt_pk_bf16_f32 v153, v66, v67
	v_cvt_pk_bf16_f32 v154, v68, v69
	v_cvt_pk_bf16_f32 v155, v70, v71
	v_cvt_pk_bf16_f32 v156, v72, v73
	v_cvt_pk_bf16_f32 v157, v74, v75
	v_cvt_pk_bf16_f32 v158, v76, v77
	v_cvt_pk_bf16_f32 v159, v78, v79
	v_mov_b32_e32 v193, v97

.LBB0_988:
	v_max_f32_e32 v0, v66, v67
	v_max_f32_e32 v136, v34, v35
	v_max3_f32 v0, v0, v68, v69
	v_max3_f32 v136, v136, v36, v37
	v_max3_f32 v0, v0, v70, v71
	v_max3_f32 v136, v136, v38, v39
	v_max3_f32 v0, v0, v72, v73
	v_max3_f32 v136, v136, v40, v41
	v_max3_f32 v0, v0, v74, v75
	v_max3_f32 v136, v136, v42, v43
	v_max3_f32 v0, v0, v76, v77
	v_max3_f32 v136, v136, v44, v45
	v_max3_f32 v0, v0, v78, v79
	v_max3_f32 v136, v136, v46, v47
	v_max3_f32 v0, v0, v80, v81
	v_max3_f32 v136, v136, v48, v49
	v_add_f32_e32 v0, v134, v0
	v_add_f32_e32 v136, v135, v136
	v_max_f32_e32 v0, v0, v136
	v_mov_b32_e32 v136, v0
	s_nop 1
	v_permlane32_swap_b32_e32 v0, v136
	v_max_f32_e32 v0, v0, v136
	v_sub_f32_e32 v136, v0, v162
	v_cmp_gt_f32_e32 vcc, s4, v136
	s_cmp_lg_u64 vcc, exec
	s_cselect_b64 s[10:11], -1, 0
	s_cmp_eq_u64 vcc, exec
	s_cbranch_scc1 .LBB0_993
	v_max_f32_e32 v163, v162, v0
	v_sub_f32_e32 v0, v162, v163
	v_exp_f32_e32 v0, v0
	s_nop 0
	v_cmp_neq_f32_e32 vcc, 1.0, v0
	s_cbranch_vccz .LBB0_991
	v_mul_f32_e32 v32, v0, v32
	v_mul_f32_e32 v33, v0, v33
	v_mul_f32_e32 v30, v0, v30
	v_mul_f32_e32 v31, v0, v31
	v_mul_f32_e32 v28, v0, v28
	v_mul_f32_e32 v29, v0, v29
	v_mul_f32_e32 v26, v0, v26
	v_mul_f32_e32 v27, v0, v27
	v_mul_f32_e32 v24, v0, v24
	v_mul_f32_e32 v25, v0, v25
	v_mul_f32_e32 v22, v0, v22
	v_mul_f32_e32 v23, v0, v23
	v_mul_f32_e32 v20, v0, v20
	v_mul_f32_e32 v21, v0, v21
	v_mul_f32_e32 v18, v0, v18
	v_mul_f32_e32 v19, v0, v19
	v_mul_f32_e32 v16, v0, v16
	v_mul_f32_e32 v17, v0, v17
	v_mul_f32_e32 v14, v0, v14
	v_mul_f32_e32 v15, v0, v15
	v_mul_f32_e32 v12, v0, v12
	v_mul_f32_e32 v13, v0, v13
	v_mul_f32_e32 v10, v0, v10
	v_mul_f32_e32 v11, v0, v11
	v_mul_f32_e32 v8, v0, v8
	v_mul_f32_e32 v9, v0, v9
	v_mul_f32_e32 v6, v0, v6
	v_mul_f32_e32 v7, v0, v7
	v_mul_f32_e32 v4, v0, v4
	v_mul_f32_e32 v5, v0, v5
	v_mul_f32_e32 v2, v0, v2
	v_mul_f32_e32 v3, v0, v3
.LBB0_991:
	v_sub_f32_e32 v114, v163, v134
	v_sub_f32_e32 v115, v163, v135
	v_sub_f32_e32 v66, v66, v114
	v_sub_f32_e32 v34, v34, v115
	v_exp_f32_e32 v66, v66
	v_exp_f32_e32 v34, v34
	v_sub_f32_e32 v67, v67, v114
	v_sub_f32_e32 v35, v35, v115
	v_exp_f32_e32 v67, v67
	v_exp_f32_e32 v35, v35
	v_sub_f32_e32 v68, v68, v114
	v_sub_f32_e32 v36, v36, v115
	v_exp_f32_e32 v68, v68
	v_exp_f32_e32 v36, v36
	v_sub_f32_e32 v69, v69, v114
	v_sub_f32_e32 v37, v37, v115
	v_exp_f32_e32 v69, v69
	v_exp_f32_e32 v37, v37
	v_sub_f32_e32 v70, v70, v114
	v_sub_f32_e32 v38, v38, v115
	v_exp_f32_e32 v70, v70
	v_exp_f32_e32 v38, v38
	v_sub_f32_e32 v71, v71, v114
	v_sub_f32_e32 v39, v39, v115
	v_add_f32_e32 v116, v67, v66
	v_add_f32_e32 v117, v35, v34
	v_exp_f32_e32 v71, v71
	v_exp_f32_e32 v39, v39
	v_sub_f32_e32 v72, v72, v114
	v_sub_f32_e32 v40, v40, v115
	v_add_f32_e32 v116, v68, v116
	v_add_f32_e32 v117, v36, v117
	v_exp_f32_e32 v72, v72
	v_exp_f32_e32 v40, v40
	v_sub_f32_e32 v73, v73, v114
	v_sub_f32_e32 v41, v41, v115
	v_add_f32_e32 v116, v69, v116
	v_add_f32_e32 v117, v37, v117
	v_exp_f32_e32 v73, v73
	v_exp_f32_e32 v41, v41
	v_sub_f32_e32 v74, v74, v114
	v_sub_f32_e32 v42, v42, v115
	v_add_f32_e32 v116, v70, v116
	v_add_f32_e32 v117, v38, v117
	v_exp_f32_e32 v74, v74
	v_exp_f32_e32 v42, v42
	v_sub_f32_e32 v75, v75, v114
	v_sub_f32_e32 v43, v43, v115
	v_add_f32_e32 v116, v71, v116
	v_add_f32_e32 v117, v39, v117
	v_exp_f32_e32 v75, v75
	v_exp_f32_e32 v43, v43
	v_sub_f32_e32 v76, v76, v114
	v_sub_f32_e32 v44, v44, v115
	v_add_f32_e32 v116, v72, v116
	v_add_f32_e32 v117, v40, v117
	v_exp_f32_e32 v76, v76
	v_exp_f32_e32 v44, v44
	v_sub_f32_e32 v77, v77, v114
	v_sub_f32_e32 v45, v45, v115
	v_add_f32_e32 v116, v73, v116
	v_add_f32_e32 v117, v41, v117
	v_exp_f32_e32 v77, v77
	v_exp_f32_e32 v45, v45
	v_sub_f32_e32 v78, v78, v114
	v_sub_f32_e32 v46, v46, v115
	v_add_f32_e32 v116, v74, v116
	v_add_f32_e32 v117, v42, v117
	v_exp_f32_e32 v78, v78
	v_exp_f32_e32 v46, v46
	v_sub_f32_e32 v79, v79, v114
	v_sub_f32_e32 v47, v47, v115
	v_add_f32_e32 v116, v75, v116
	v_add_f32_e32 v117, v43, v117
	v_exp_f32_e32 v79, v79
	v_exp_f32_e32 v47, v47
	v_sub_f32_e32 v80, v80, v114
	v_sub_f32_e32 v48, v48, v115
	v_add_f32_e32 v116, v76, v116
	v_add_f32_e32 v117, v44, v117
	v_exp_f32_e32 v80, v80
	v_exp_f32_e32 v48, v48
	v_sub_f32_e32 v81, v81, v114
	v_sub_f32_e32 v49, v49, v115
	v_add_f32_e32 v116, v77, v116
	v_add_f32_e32 v117, v45, v117
	v_exp_f32_e32 v81, v81
	v_exp_f32_e32 v49, v49
	v_add_f32_e32 v116, v78, v116
	v_add_f32_e32 v117, v46, v117
	v_add_f32_e32 v116, v79, v116
	v_add_f32_e32 v117, v47, v117
	v_add_f32_e32 v114, v80, v116
	v_add_f32_e32 v115, v48, v117
	v_add_f32_e32 v114, v81, v114
	v_add_f32_e32 v115, v49, v115
	v_add_f32_e32 v134, v114, v115
	v_fmac_f32_e32 v134, v147, v0
	v_cvt_pk_bf16_f32 v114, v66, v67
	v_cvt_pk_bf16_f32 v115, v68, v69
	v_cvt_pk_bf16_f32 v116, v70, v71
	v_cvt_pk_bf16_f32 v117, v72, v73
	v_cvt_pk_bf16_f32 v118, v74, v75
	v_cvt_pk_bf16_f32 v119, v76, v77
	v_cvt_pk_bf16_f32 v120, v78, v79
	v_cvt_pk_bf16_f32 v121, v80, v81
	v_cvt_pk_bf16_f32 v122, v34, v35
	v_cvt_pk_bf16_f32 v123, v36, v37
	v_cvt_pk_bf16_f32 v124, v38, v39
	v_cvt_pk_bf16_f32 v125, v40, v41
	v_cvt_pk_bf16_f32 v126, v42, v43
	v_cvt_pk_bf16_f32 v127, v44, v45
	v_cvt_pk_bf16_f32 v128, v46, v47
	v_cvt_pk_bf16_f32 v129, v48, v49
	v_mov_b32_e32 v147, v134
	s_andn2_b64 vcc, exec, s[10:11]
	s_cbranch_vccz .LBB0_994
	s_branch .LBB0_995

.LBB0_1004:
	v_max_f32_e32 v0, v82, v83
	v_max_f32_e32 v136, v50, v51
	v_max3_f32 v0, v0, v84, v85
	v_max3_f32 v136, v136, v52, v53
	v_max3_f32 v0, v0, v86, v87
	v_max3_f32 v136, v136, v54, v55
	v_max3_f32 v0, v0, v88, v89
	v_max3_f32 v136, v136, v56, v57
	v_max3_f32 v0, v0, v90, v91
	v_max3_f32 v136, v136, v58, v59
	v_max3_f32 v0, v0, v92, v93
	v_max3_f32 v136, v136, v60, v61
	v_max3_f32 v0, v0, v94, v95
	v_max3_f32 v136, v136, v62, v63
	v_max3_f32 v0, v0, v96, v97
	v_max3_f32 v136, v136, v64, v65
	v_add_f32_e32 v0, v134, v0
	v_add_f32_e32 v136, v135, v136
	v_max_f32_e32 v0, v0, v136
	v_mov_b32_e32 v136, v0
	s_nop 1
	v_permlane32_swap_b32_e32 v0, v136
	v_max_f32_e32 v0, v0, v136
	v_sub_f32_e32 v136, v0, v163
	v_cmp_gt_f32_e32 vcc, s4, v136
	s_cmp_lg_u64 vcc, exec
	s_cselect_b64 s[8:9], -1, 0
	s_cmp_eq_u64 vcc, exec
	s_cbranch_scc1 .LBB0_1009
	v_max_f32_e32 v162, v163, v0
	v_sub_f32_e32 v0, v163, v162
	v_exp_f32_e32 v0, v0
	s_nop 0
	v_cmp_neq_f32_e32 vcc, 1.0, v0
	s_cbranch_vccz .LBB0_1007
	v_mul_f32_e32 v32, v0, v32
	v_mul_f32_e32 v33, v0, v33
	v_mul_f32_e32 v30, v0, v30
	v_mul_f32_e32 v31, v0, v31
	v_mul_f32_e32 v28, v0, v28
	v_mul_f32_e32 v29, v0, v29
	v_mul_f32_e32 v26, v0, v26
	v_mul_f32_e32 v27, v0, v27
	v_mul_f32_e32 v24, v0, v24
	v_mul_f32_e32 v25, v0, v25
	v_mul_f32_e32 v22, v0, v22
	v_mul_f32_e32 v23, v0, v23
	v_mul_f32_e32 v20, v0, v20
	v_mul_f32_e32 v21, v0, v21
	v_mul_f32_e32 v18, v0, v18
	v_mul_f32_e32 v19, v0, v19
	v_mul_f32_e32 v16, v0, v16
	v_mul_f32_e32 v17, v0, v17
	v_mul_f32_e32 v14, v0, v14
	v_mul_f32_e32 v15, v0, v15
	v_mul_f32_e32 v12, v0, v12
	v_mul_f32_e32 v13, v0, v13
	v_mul_f32_e32 v10, v0, v10
	v_mul_f32_e32 v11, v0, v11
	v_mul_f32_e32 v8, v0, v8
	v_mul_f32_e32 v9, v0, v9
	v_mul_f32_e32 v6, v0, v6
	v_mul_f32_e32 v7, v0, v7
	v_mul_f32_e32 v4, v0, v4
	v_mul_f32_e32 v5, v0, v5
	v_mul_f32_e32 v2, v0, v2
	v_mul_f32_e32 v3, v0, v3
.LBB0_1007:
	v_sub_f32_e32 v114, v162, v134
	v_sub_f32_e32 v115, v162, v135
	v_sub_f32_e32 v82, v82, v114
	v_sub_f32_e32 v50, v50, v115
	v_exp_f32_e32 v82, v82
	v_exp_f32_e32 v50, v50
	v_sub_f32_e32 v83, v83, v114
	v_sub_f32_e32 v51, v51, v115
	v_exp_f32_e32 v83, v83
	v_exp_f32_e32 v51, v51
	v_sub_f32_e32 v84, v84, v114
	v_sub_f32_e32 v52, v52, v115
	v_exp_f32_e32 v84, v84
	v_exp_f32_e32 v52, v52
	v_sub_f32_e32 v85, v85, v114
	v_sub_f32_e32 v53, v53, v115
	v_exp_f32_e32 v85, v85
	v_exp_f32_e32 v53, v53
	v_sub_f32_e32 v86, v86, v114
	v_sub_f32_e32 v54, v54, v115
	v_exp_f32_e32 v86, v86
	v_exp_f32_e32 v54, v54
	v_sub_f32_e32 v87, v87, v114
	v_sub_f32_e32 v55, v55, v115
	v_add_f32_e32 v116, v83, v82
	v_add_f32_e32 v117, v51, v50
	v_exp_f32_e32 v87, v87
	v_exp_f32_e32 v55, v55
	v_sub_f32_e32 v88, v88, v114
	v_sub_f32_e32 v56, v56, v115
	v_add_f32_e32 v116, v84, v116
	v_add_f32_e32 v117, v52, v117
	v_exp_f32_e32 v88, v88
	v_exp_f32_e32 v56, v56
	v_sub_f32_e32 v89, v89, v114
	v_sub_f32_e32 v57, v57, v115
	v_add_f32_e32 v116, v85, v116
	v_add_f32_e32 v117, v53, v117
	v_exp_f32_e32 v89, v89
	v_exp_f32_e32 v57, v57
	v_sub_f32_e32 v90, v90, v114
	v_sub_f32_e32 v58, v58, v115
	v_add_f32_e32 v116, v86, v116
	v_add_f32_e32 v117, v54, v117
	v_exp_f32_e32 v90, v90
	v_exp_f32_e32 v58, v58
	v_sub_f32_e32 v91, v91, v114
	v_sub_f32_e32 v59, v59, v115
	v_add_f32_e32 v116, v87, v116
	v_add_f32_e32 v117, v55, v117
	v_exp_f32_e32 v91, v91
	v_exp_f32_e32 v59, v59
	v_sub_f32_e32 v92, v92, v114
	v_sub_f32_e32 v60, v60, v115
	v_add_f32_e32 v116, v88, v116
	v_add_f32_e32 v117, v56, v117
	v_exp_f32_e32 v92, v92
	v_exp_f32_e32 v60, v60
	v_sub_f32_e32 v93, v93, v114
	v_sub_f32_e32 v61, v61, v115
	v_add_f32_e32 v116, v89, v116
	v_add_f32_e32 v117, v57, v117
	v_exp_f32_e32 v93, v93
	v_exp_f32_e32 v61, v61
	v_sub_f32_e32 v94, v94, v114
	v_sub_f32_e32 v62, v62, v115
	v_add_f32_e32 v116, v90, v116
	v_add_f32_e32 v117, v58, v117
	v_exp_f32_e32 v94, v94
	v_exp_f32_e32 v62, v62
	v_sub_f32_e32 v95, v95, v114
	v_sub_f32_e32 v63, v63, v115
	v_add_f32_e32 v116, v91, v116
	v_add_f32_e32 v117, v59, v117
	v_exp_f32_e32 v95, v95
	v_exp_f32_e32 v63, v63
	v_sub_f32_e32 v96, v96, v114
	v_sub_f32_e32 v64, v64, v115
	v_add_f32_e32 v116, v92, v116
	v_add_f32_e32 v117, v60, v117
	v_exp_f32_e32 v96, v96
	v_exp_f32_e32 v64, v64
	v_sub_f32_e32 v97, v97, v114
	v_sub_f32_e32 v65, v65, v115
	v_add_f32_e32 v116, v93, v116
	v_add_f32_e32 v117, v61, v117
	v_exp_f32_e32 v97, v97
	v_exp_f32_e32 v65, v65
	v_add_f32_e32 v116, v94, v116
	v_add_f32_e32 v117, v62, v117
	v_add_f32_e32 v116, v95, v116
	v_add_f32_e32 v117, v63, v117
	v_add_f32_e32 v114, v96, v116
	v_add_f32_e32 v115, v64, v117
	v_add_f32_e32 v114, v97, v114
	v_add_f32_e32 v115, v65, v115
	v_add_f32_e32 v134, v114, v115
	v_fmac_f32_e32 v134, v147, v0
	v_cvt_pk_bf16_f32 v114, v82, v83
	v_cvt_pk_bf16_f32 v115, v84, v85
	v_cvt_pk_bf16_f32 v116, v86, v87
	v_cvt_pk_bf16_f32 v117, v88, v89
	v_cvt_pk_bf16_f32 v118, v90, v91
	v_cvt_pk_bf16_f32 v119, v92, v93
	v_cvt_pk_bf16_f32 v120, v94, v95
	v_cvt_pk_bf16_f32 v121, v96, v97
	v_cvt_pk_bf16_f32 v122, v50, v51
	v_cvt_pk_bf16_f32 v123, v52, v53
	v_cvt_pk_bf16_f32 v124, v54, v55
	v_cvt_pk_bf16_f32 v125, v56, v57
	v_cvt_pk_bf16_f32 v126, v58, v59
	v_cvt_pk_bf16_f32 v127, v60, v61
	v_cvt_pk_bf16_f32 v128, v62, v63
	v_cvt_pk_bf16_f32 v129, v64, v65
	v_mov_b32_e32 v147, v134
	s_andn2_b64 vcc, exec, s[8:9]
	s_cbranch_vccz .LBB0_1010
	s_branch .LBB0_1011
